# up-proj now visits column tiles of each panel group in descending order so its last round leaves the first K columns of the hidden tensor hot for the down-proj
# baseline (speedup 1.0000x reference)
; #define PG8_WAIT_V(n) asm volatile("s_waitcnt vmcnt(" #n ")" ::: "memory")
;     __device__ bool next(int i, Unit& u) const {
;         const long L = (long)i * G + c; if (L >= nwg) return false;
;         int wgid = (int)L; { const int q = nwg / NXCD, r = nwg % NXCD, xcd = wgid % NXCD, off = wgid / NXCD; wgid = (xcd < r ? xcd * (q + 1) : r * (q + 1) + (xcd - r) * q) + off; }
;         const int nig = WGM * nN, gid = wgid / nig, fm = gid * WGM, gsz = (nM - fm) < WGM ? (nM - fm) : WGM;
;         u.pm = fm + ((wgid % nig) % gsz); u.pn = (wgid % nig) / gsz; u.ko = 0; return true;
;     }
; template <class Epi, bool SP2, class Sched>
; __device__ __forceinline__ void gemm_phase(LAS unsigned char* lds, const Gemm g, const Sched& S, const Epi& E) {
;     ...
;     const int wid = __builtin_amdgcn_readfirstlane(tid >> 6), lane = tid & 63, wr = wid >> 2, wc = wid & 3, fr = lane & 15, fq = lane >> 4;
;     const int K = g.K, nt = K / BK;
;     unsigned voffA[2], voffB[2];
; #pragma unroll
;     for (int i = 0; i < 2; ++i) { int R, C; stage_rc(tid * 16 + i * 8192, R, C); const int Rb = Epi::PERM ? ((R & ~31) + perm32(R & 31)) : R;
;         voffA[i] = (unsigned)(R * g.lda + C) * 2u; voffB[i] = (unsigned)(Rb * g.ldb + C) * 2u; }
;     const size_t kstep = (size_t)(BK * 2);
;     const size_t hstep = (size_t)HALF * g.lda * 2, hstepB = (size_t)HALF * g.ldb * 2;
;     const size_t tstep = 2 * hstep, tstepB = 2 * hstepB;
;     const unsigned ldsw = (unsigned)wid * 1024u;
;     const int aoff = lds_byte(wr * 64 + fr, fq * 8), boff = lds_byte(wc * 32 + fr, fq * 8);
;     ...
;     Unit cur, nxt; int ui = 0;
;     if (!S.next(0, cur)) return;
;     f32x4 acc[2][2][4][2];
; #pragma unroll
;     for (int a = 0; a < 2; ++a)
; #pragma unroll
;         for (int b = 0; b < 2; ++b)
; #pragma unroll
;             for (int m = 0; m < 4; ++m)
; #pragma unroll
;                 for (int n = 0; n < 2; ++n) acc[a][b][m][n] = (f32x4){0.f, 0.f, 0.f, 0.f};
;     bf16x8 At[4][2], B0[2][2], B1[2][2];
;     const char* cA = (const char*)g.A + (size_t)cur.pm * tstep + cur.ko; const char* cB = (const char*)g.Bt + (size_t)cur.pn * tstepB + cur.ko;
;     if constexpr (SP2) {
;         PG8_STAGE(PG8_SB(0, 0), cB, voffB); PG8_STAGE(PG8_SB(0, 1), cB + hstepB, voffB); PG8_STAGE(PG8_SA(0, 0), cA, voffA); PG8_STAGE(PG8_SA(0, 1), cA + hstep, voffA);
;         if (wr == 1) PG8_BAR;
;         PG8_WAIT_V(2); PG8_BAR;
.LBB0_1030:
	s_or_b64 exec, exec, s[0:1]
	s_mov_b64 s[0:1], s[74:75]
	s_mov_b32 s62, s83
	s_mov_b32 s12, s14
	s_mov_b32 s64, s18
	v_mov_b32_e32 v14, v242
	s_waitcnt lgkmcnt(0)
	s_barrier
	s_cmpk_lt_i32 s62, 0x1040
	s_nop 0
	v_readfirstlane_b32 s7, v14
	s_cbranch_scc0 .LBB0_1046
	v_lshlrev_b32_e32 v0, 4, v14
	v_add_u32_e32 v1, 0x2000, v0
	v_ashrrev_i32_e32 v2, 31, v1
	v_lshrrev_b32_e32 v2, 22, v2
	v_add_u32_e32 v2, v1, v2
	v_ashrrev_i32_e32 v8, 10, v2
	v_mul_i32_i24_e32 v2, 0x400, v8
	v_sub_u32_e32 v1, v1, v2
	v_lshrrev_b32_e32 v2, 4, v1
	s_mul_i32 s3, s12, 0x1f00000
	v_bitop3_b32 v1, v2, v1, 32 bitop3:0x6c
	s_mul_hi_i32 s2, s12, 0x1f00000
	s_add_u32 s3, s0, s3
	v_ashrrev_i32_e32 v2, 31, v1
	s_addc_u32 s2, s1, s2
	v_lshrrev_b32_e32 v2, 26, v2
	s_add_u32 s65, s0, 0x4200000
	v_add_u32_e32 v2, v1, v2
	v_lshlrev_b32_e32 v3, 3, v8
	s_addc_u32 s68, s1, 0
	v_ashrrev_i32_e32 v9, 6, v2
	v_and_b32_e32 v3, -16, v3
	s_add_u32 s69, s3, 0x1280000
	v_add_u32_e32 v3, v9, v3
	s_addc_u32 s72, s2, 0
	v_and_b32_e32 v4, 3, v9
	s_mov_b32 s2, 0x1fffe0
	v_lshrrev_b32_e32 v5, 2, v3
	v_lshlrev_b32_e32 v6, 1, v3
	v_and_b32_e32 v2, 0xc0, v2
	v_and_or_b32 v4, v3, s2, v4
	v_and_b32_e32 v5, 4, v5
	v_and_b32_e32 v6, 24, v6
	v_sub_u32_e32 v1, v1, v2
	v_or3_b32 v4, v4, v5, v6
	v_lshlrev_b32_e32 v5, 5, v8
	v_ashrrev_i16_sdwa v1, v244, sext(v1) dst_sel:DWORD dst_unused:UNUSED_PAD src0_sel:DWORD src1_sel:BYTE_0
	v_and_b32_e32 v5, 32, v5
	v_bfe_i32 v10, v1, 0, 16
	v_add_lshl_u32 v1, v5, v10, 1
	v_lshl_add_u32 v130, v4, 11, v1
	v_lshl_add_u32 v132, v3, 11, v1
	v_bfe_i32 v1, v14, 27, 1
	v_lshrrev_b32_e32 v1, 22, v1
	v_add_u32_e32 v1, v0, v1
	v_and_b32_e32 v1, 0xfffffc00, v1
	v_sub_u32_e32 v0, v0, v1
	v_lshrrev_b32_e32 v1, 4, v0
	v_ashrrev_i32_e32 v2, 31, v14
	v_bitop3_b32 v0, v1, v0, 32 bitop3:0x6c
	v_lshrrev_b32_e32 v2, 26, v2
	v_ashrrev_i32_e32 v1, 31, v0
	v_add_u32_e32 v2, v14, v2
	v_lshrrev_b32_e32 v1, 26, v1
	v_ashrrev_i32_e32 v12, 6, v2
	v_add_u32_e32 v1, v0, v1
	v_lshlrev_b32_e32 v2, 3, v12
	v_ashrrev_i32_e32 v11, 6, v1
	v_and_b32_e32 v2, -16, v2
	s_ashr_i32 s73, s62, 31
	v_add_u32_e32 v2, v11, v2
	v_and_b32_e32 v3, 3, v11
	v_and_or_b32 v3, v2, s2, v3
	s_lshr_b32 s2, s73, 29
	s_add_i32 s2, s62, s2
	s_ashr_i32 s8, s7, 6
	s_ashr_i32 s3, s2, 3
	s_and_b32 s2, s2, -8
	s_ashr_i32 s9, s7, 8
	s_lshl_b32 s79, s8, 10
	s_sub_i32 s2, s62, s2
	s_cmp_lt_i32 s2, 0
	s_movk_i32 s4, 0x200
	s_cselect_b32 s4, s4, 0x200
	s_mul_i32 s2, s2, s4
	s_add_i32 s2, s2, s3
	s_ashr_i32 s3, s2, 31
	s_lshr_b32 s3, s3, 25
	v_lshrrev_b32_e32 v4, 2, v2
	v_lshlrev_b32_e32 v5, 1, v2
	v_and_b32_e32 v1, 0xc0, v1
	s_add_i32 s3, s2, s3
	v_and_b32_e32 v4, 4, v4
	v_and_b32_e32 v5, 24, v5
	v_sub_u32_e32 v0, v0, v1
	s_ashr_i32 s4, s3, 7
	v_or3_b32 v3, v3, v4, v5
	v_lshlrev_b32_e32 v4, 5, v12
	v_ashrrev_i16_sdwa v0, v244, sext(v0) dst_sel:DWORD dst_unused:UNUSED_PAD src0_sel:DWORD src1_sel:BYTE_0
	s_lshl_b32 s4, s4, 3
	v_and_b32_e32 v4, 32, v4
	v_bfe_i32 v13, v0, 0, 16
	s_sub_i32 s5, 0x104, s4
	v_add_lshl_u32 v0, v4, v13, 1
	s_min_u32 s5, s5, 8
	s_and_b32 s3, s3, 0xffffff80
	v_lshl_add_u32 v64, v3, 11, v0
	s_sub_i32 s10, s2, s3
	v_cvt_f32_ubyte0_e32 v3, s5
	v_cvt_f32_i32_e32 v1, s10
	v_rcp_iflag_f32_e32 v4, v3
	s_waitcnt vmcnt(0)
	v_lshl_add_u32 v134, v2, 11, v0
	s_ashr_i32 s2, s10, 30
	s_or_b32 s6, s2, 1
	v_mul_f32_e32 v0, v1, v4
	v_trunc_f32_e32 v0, v0
	v_fma_f32 v1, -v0, v3, v1
	v_cvt_i32_f32_e32 v0, v0
	v_cmp_ge_f32_e64 s[2:3], |v1|, v3
	s_and_b64 s[2:3], s[2:3], exec
	s_cselect_b32 s2, s6, 0
	v_readfirstlane_b32 s3, v0
	s_add_i32 s6, s3, s2
	s_mul_i32 s2, s6, s5
	s_sub_i32 s2, s10, s2
	s_sub_i32 s6, 15, s6
	s_sext_i32_i8 s2, s2
	s_add_i32 s4, s4, s2
	s_ashr_i32 s5, s4, 31
	s_bfe_i64 s[10:11], s[6:7], 0x80000
	s_lshl_b64 s[2:3], s[4:5], 19
	s_lshl_b64 s[10:11], s[10:11], 19
	s_add_u32 s10, s69, s10
	s_addc_u32 s11, s72, s11
	s_add_i32 s83, s79, 0
	s_add_i32 m0, s83, 0x10000
	v_mov_b32_e32 v131, v65
	global_load_lds_dwordx4 v64, s[10:11]
	s_add_i32 m0, s83, 0x12000
	s_add_u32 s14, s10, 0x40000
	global_load_lds_dwordx4 v130, s[10:11]
	s_addc_u32 s15, s11, 0
	s_add_i32 m0, s83, 0x14000
	v_mov_b32_e32 v135, v65
	global_load_lds_dwordx4 v64, s[14:15]
	s_add_i32 m0, s83, 0x16000
	s_add_u32 s16, s65, s2
	s_addc_u32 s17, s68, s3
	s_add_i32 s90, s83, 0x2000
	global_load_lds_dwordx4 v130, s[14:15]
	s_mov_b32 m0, s83
	s_add_u32 s2, s16, 0x40000
	global_load_lds_dwordx4 v134, s[16:17]
	s_mov_b32 m0, s90
	s_addc_u32 s3, s17, 0
	s_add_i32 s91, s83, 0x4000
	global_load_lds_dwordx4 v132, s[16:17]
	s_mov_b32 m0, s91
	s_add_i32 s92, s83, 0x6000
	global_load_lds_dwordx4 v134, s[2:3]
	s_mov_b32 m0, s92
	v_mov_b32_e32 v133, v65
	global_load_lds_dwordx4 v132, s[2:3]
	s_cmp_eq_u32 s9, 1
	v_lshl_add_u64 v[6:7], s[10:11], 0, v[64:65]
	v_lshl_add_u64 v[4:5], s[10:11], 0, v[130:131]
	v_lshl_add_u64 v[0:1], s[16:17], 0, v[134:135]
	s_cselect_b64 s[2:3], -1, 0
	s_cmp_lg_u32 s9, 1
	v_lshl_add_u64 v[2:3], s[16:17], 0, v[132:133]
	s_cbranch_scc1 .LBB0_1033
	s_barrier

;     __device__ bool next(int i, Unit& u) const {
;         const long L = (long)i * G + c; if (L >= nwg) return false;
;         int wgid = (int)L; { const int q = nwg / NXCD, r = nwg % NXCD, xcd = wgid % NXCD, off = wgid / NXCD; wgid = (xcd < r ? xcd * (q + 1) : r * (q + 1) + (xcd - r) * q) + off; }
;         const int nig = WGM * nN, gid = wgid / nig, fm = gid * WGM, gsz = (nM - fm) < WGM ? (nM - fm) : WGM;
;         u.pm = fm + ((wgid % nig) % gsz); u.pn = (wgid % nig) / gsz; u.ko = 0; return true;
;     }
; template <class Epi, bool SP2, class Sched>
; __device__ __forceinline__ void gemm_phase(LAS unsigned char* lds, const Gemm g, const Sched& S, const Epi& E) {
;     ...
;         const bool has_next = S.next(ui + 1, nxt);
;         const char* nA = has_next ? (const char*)g.A + (size_t)nxt.pm * tstep + nxt.ko : cA; const char* nB = has_next ? (const char*)g.Bt + (size_t)nxt.pn * tstepB + nxt.ko : cB;
.LBB0_1036:
	s_add_i32 s96, s96, 1
	s_mul_i32 s0, s96, s93
	s_mul_hi_u32 s1, s96, s64
	s_add_i32 s1, s1, s0
	s_mul_i32 s0, s96, s64
	s_add_u32 s6, s0, s62
	s_addc_u32 s7, s1, s73
	v_cmp_gt_i64_e32 vcc, s[6:7], v[208:209]
	v_cmp_lt_i64_e64 s[0:1], s[6:7], v[206:207]
	s_cbranch_vccnz .LBB0_1038
	s_ashr_i32 s7, s6, 31
	s_lshr_b32 s7, s7, 29
	s_add_i32 s7, s6, s7
	s_ashr_i32 s8, s7, 3
	s_and_b32 s7, s7, -8
	s_sub_i32 s6, s6, s7
	s_cmp_lt_i32 s6, 0
	s_movk_i32 s7, 0x200
	s_cselect_b32 s7, s7, 0x200
	s_mul_i32 s6, s6, s7
	s_add_i32 s6, s6, s8
	s_mul_i32 s7, s96, s64
	s_add_i32 s7, s7, s62
	s_cmpk_lt_i32 s7, 0x1000
	s_cselect_b32 s6, s6, s7
	s_ashr_i32 s7, s6, 31
	s_lshr_b32 s7, s7, 25
	s_add_i32 s7, s6, s7
	s_ashr_i32 s8, s7, 7
	s_lshl_b32 s8, s8, 3
	s_sub_i32 s9, 0x104, s8
	s_min_i32 s9, s9, 8
	s_abs_i32 s12, s9
	v_cvt_f32_u32_e32 v0, s12
	s_sub_i32 s14, 0, s12
	s_and_b32 s7, s7, 0xffffff80
	s_sub_i32 s6, s6, s7
	v_rcp_iflag_f32_e32 v0, v0
	s_abs_i32 s7, s6
	s_xor_b32 s13, s6, s9
	s_ashr_i32 s13, s13, 31
	v_mul_f32_e32 v0, 0x4f7ffffe, v0
	v_cvt_u32_f32_e32 v0, v0
	s_nop 0
	v_readfirstlane_b32 s15, v0
	s_mul_i32 s14, s14, s15
	s_mul_hi_u32 s14, s15, s14
	s_add_i32 s15, s15, s14
	s_mul_hi_u32 s14, s7, s15
	s_mul_i32 s15, s14, s12
	s_sub_i32 s7, s7, s15
	s_add_i32 s18, s14, 1
	s_sub_i32 s15, s7, s12
	s_cmp_ge_u32 s7, s12
	s_cselect_b32 s14, s18, s14
	s_cselect_b32 s7, s15, s7
	s_add_i32 s15, s14, 1
	s_cmp_ge_u32 s7, s12
	s_cselect_b32 s7, s15, s14
	s_xor_b32 s7, s7, s13
	s_sub_i32 s60, s7, s13
	s_mul_i32 s7, s60, s9
	s_sub_i32 s6, s6, s7
	s_add_i32 s84, s8, s6
	s_sub_i32 s60, 15, s60
